# inter-chunk scan: the wave-uniform chunk decays come from scalar loads instead of 64 vector loads per wave
# baseline (speedup 1.0000x reference)
; __device__ __forceinline__ float bf2f(bf16 v) { return __uint_as_float(((unsigned)v) << 16); }
; __device__ __forceinline__ unsigned f2bfu(float f) { return (unsigned)__builtin_bit_cast(unsigned short, (__bf16)f); }
; __global__ void __launch_bounds__(NTHR, 2) k_main(Args a) {
;     ...
;         for (int idx = gtid; idx < 2 * 8 * 8192; idx += gthreads) {
;             const int pn = idx & 8191, h = (idx >> 13) & 7, b = idx >> 16;
;             float run = 0.f;
; #pragma unroll 1
;             for (int c0 = 0; c0 < 64; c0 += 8) {
;                 float st[8], dc[8];
; #pragma unroll
;                 for (int j = 0; j < 8; ++j) { const int bch = (b * 64 + c0 + j) * 8 + h; st[j] = bf2f(__builtin_nontemporal_load(&STATES[(size_t)bch * 8192 + pn])); dc[j] = CDEC[bch]; }
; #pragma unroll
;                 for (int j = 0; j < 8; ++j) { const int bch = (b * 64 + c0 + j) * 8 + h; __builtin_amdgcn_raw_buffer_store_b16((short)f2bfu(run), rsPV, (int)(((unsigned)bch * 8192u + (unsigned)pn) * 2u), 0, 16); run = dc[j] * run + st[j]; }
;             }
;         }
.LBB0_377:
	v_and_b32_e32 v2, 0x1fff, v8
	v_ashrrev_i32_e32 v10, 10, v8
	v_lshlrev_b32_e32 v2, 1, v2
	v_lshl_add_u64 v[4:5], s[58:59], 0, v[2:3]
	v_lshrrev_b32_e32 v2, 6, v10
	v_bfe_u32 v6, v8, 13, 3
	v_and_b32_e32 v7, 0x1fffe, v9
	v_lshlrev_b32_e32 v10, 9, v2
	v_lshlrev_b32_e32 v2, 23, v2
	v_or3_b32 v6, v10, v6, 56
	v_or3_b32 v2, v2, v7, s10
	s_mov_b32 s12, -8
	v_mov_b32_e32 v10, 0
	v_subrev_u32_e32 v46, 56, v6
	v_and_b32_e32 v47, 0x1fff, v8
	v_lshlrev_b32_e32 v47, 1, v47
	v_lshl_add_u32 v47, v46, 14, v47
	v_lshlrev_b32_e32 v50, 2, v46
	v_add_u32_e32 v51, 0xfff20000, v2
	v_readfirstlane_b32 s44, v50
	s_nop 3
	s_add_u32 s46, s82, s44
	s_addc_u32 s47, s83, 0
	global_load_ushort v128, v47, s[58:59] nt
	v_add_u32_e32 v53, 0x20000, v47
	global_load_ushort v129, v53, s[58:59] nt
	v_add_u32_e32 v53, 0x40000, v47
	global_load_ushort v130, v53, s[58:59] nt
	v_add_u32_e32 v53, 0x60000, v47
	global_load_ushort v131, v53, s[58:59] nt
	v_add_u32_e32 v53, 0x80000, v47
	global_load_ushort v132, v53, s[58:59] nt
	v_add_u32_e32 v53, 0xa0000, v47
	global_load_ushort v133, v53, s[58:59] nt
	v_add_u32_e32 v53, 0xc0000, v47
	global_load_ushort v134, v53, s[58:59] nt
	v_add_u32_e32 v53, 0xe0000, v47
	global_load_ushort v135, v53, s[58:59] nt
	v_add_u32_e32 v53, 0x100000, v47
	global_load_ushort v136, v53, s[58:59] nt
	v_add_u32_e32 v53, 0x120000, v47
	global_load_ushort v137, v53, s[58:59] nt
	v_add_u32_e32 v53, 0x140000, v47
	global_load_ushort v138, v53, s[58:59] nt
	v_add_u32_e32 v53, 0x160000, v47
	global_load_ushort v139, v53, s[58:59] nt
	v_add_u32_e32 v53, 0x180000, v47
	global_load_ushort v140, v53, s[58:59] nt
	v_add_u32_e32 v53, 0x1a0000, v47
	global_load_ushort v141, v53, s[58:59] nt
	v_add_u32_e32 v53, 0x1c0000, v47
	global_load_ushort v142, v53, s[58:59] nt
	v_add_u32_e32 v53, 0x1e0000, v47
	global_load_ushort v143, v53, s[58:59] nt
	s_load_dword s64, s[46:47], 0x0
	s_load_dword s65, s[46:47], 0x20
	s_load_dword s66, s[46:47], 0x40
	s_load_dword s67, s[46:47], 0x60
	s_load_dword s68, s[46:47], 0x80
	s_load_dword s69, s[46:47], 0xa0
	s_load_dword s70, s[46:47], 0xc0
	s_load_dword s71, s[46:47], 0xe0
	s_load_dword s72, s[46:47], 0x100
	s_load_dword s73, s[46:47], 0x120
	s_load_dword s74, s[46:47], 0x140
	s_load_dword s75, s[46:47], 0x160
	s_load_dword s76, s[46:47], 0x180
	s_load_dword s77, s[46:47], 0x1a0
	s_load_dword s78, s[46:47], 0x1c0
	s_load_dword s79, s[46:47], 0x1e0
	v_add_u32_e32 v53, 0x200000, v47
	global_load_ushort v144, v53, s[58:59] nt
	v_add_u32_e32 v53, 0x220000, v47
	global_load_ushort v145, v53, s[58:59] nt
	v_add_u32_e32 v53, 0x240000, v47
	global_load_ushort v146, v53, s[58:59] nt
	v_add_u32_e32 v53, 0x260000, v47
	global_load_ushort v147, v53, s[58:59] nt
	v_add_u32_e32 v53, 0x280000, v47
	global_load_ushort v148, v53, s[58:59] nt
	v_add_u32_e32 v53, 0x2a0000, v47
	global_load_ushort v149, v53, s[58:59] nt
	v_add_u32_e32 v53, 0x2c0000, v47
	global_load_ushort v150, v53, s[58:59] nt
	v_add_u32_e32 v53, 0x2e0000, v47
	global_load_ushort v151, v53, s[58:59] nt
	v_add_u32_e32 v53, 0x300000, v47
	global_load_ushort v152, v53, s[58:59] nt
	v_add_u32_e32 v53, 0x320000, v47
	global_load_ushort v153, v53, s[58:59] nt
	v_add_u32_e32 v53, 0x340000, v47
	global_load_ushort v154, v53, s[58:59] nt
	v_add_u32_e32 v53, 0x360000, v47
	global_load_ushort v155, v53, s[58:59] nt
	v_add_u32_e32 v53, 0x380000, v47
	global_load_ushort v156, v53, s[58:59] nt
	v_add_u32_e32 v53, 0x3a0000, v47
	global_load_ushort v157, v53, s[58:59] nt
	v_add_u32_e32 v53, 0x3c0000, v47
	global_load_ushort v158, v53, s[58:59] nt
	v_add_u32_e32 v53, 0x3e0000, v47
	global_load_ushort v159, v53, s[58:59] nt
	s_waitcnt lgkmcnt(0)
	s_load_dword s21, s[46:47], 0x200
	s_load_dword s22, s[46:47], 0x220
	s_load_dword s23, s[46:47], 0x240
	s_load_dword s24, s[46:47], 0x260
	s_load_dword s25, s[46:47], 0x280
	s_load_dword s26, s[46:47], 0x2a0
	s_load_dword s27, s[46:47], 0x2c0
	s_load_dword s37, s[46:47], 0x2e0
	s_load_dword s38, s[46:47], 0x300
	s_load_dword s39, s[46:47], 0x320
	s_load_dword s40, s[46:47], 0x340
	s_load_dword s41, s[46:47], 0x360
	s_load_dword s45, s[46:47], 0x380
	s_load_dword s48, s[46:47], 0x3a0
	s_load_dword s49, s[46:47], 0x3c0
	s_load_dword s32, s[46:47], 0x3e0
	v_cvt_pk_bf16_f32 v52, v10, v10
	buffer_store_short v52, v51, s[4:7], 0 offen sc1
	s_waitcnt vmcnt(32)
	v_lshlrev_b32_e32 v128, 16, v128
	v_fmac_f32_e32 v128, s64, v10
	v_mov_b32_e32 v10, v128
	v_cvt_pk_bf16_f32 v52, v10, v10
	s_mov_b32 s13, 0x20000
	buffer_store_short v52, v51, s[4:7], s13 offen sc1
	s_waitcnt vmcnt(32)
	v_lshlrev_b32_e32 v129, 16, v129
	v_fmac_f32_e32 v129, s65, v10
	v_mov_b32_e32 v10, v129
	v_cvt_pk_bf16_f32 v52, v10, v10
	s_mov_b32 s13, 0x40000
	buffer_store_short v52, v51, s[4:7], s13 offen sc1
	s_waitcnt vmcnt(32)
	v_lshlrev_b32_e32 v130, 16, v130
	v_fmac_f32_e32 v130, s66, v10
	v_mov_b32_e32 v10, v130
	v_cvt_pk_bf16_f32 v52, v10, v10
	s_mov_b32 s13, 0x60000
	buffer_store_short v52, v51, s[4:7], s13 offen sc1
	s_waitcnt vmcnt(32)
	v_lshlrev_b32_e32 v131, 16, v131
	v_fmac_f32_e32 v131, s67, v10
	v_mov_b32_e32 v10, v131
	v_cvt_pk_bf16_f32 v52, v10, v10
	s_mov_b32 s13, 0x80000
	buffer_store_short v52, v51, s[4:7], s13 offen sc1
	s_waitcnt vmcnt(32)
	v_lshlrev_b32_e32 v132, 16, v132
	v_fmac_f32_e32 v132, s68, v10
	v_mov_b32_e32 v10, v132
	v_cvt_pk_bf16_f32 v52, v10, v10
	s_mov_b32 s13, 0xa0000
	buffer_store_short v52, v51, s[4:7], s13 offen sc1
	s_waitcnt vmcnt(32)
	v_lshlrev_b32_e32 v133, 16, v133
	v_fmac_f32_e32 v133, s69, v10
	v_mov_b32_e32 v10, v133
	v_cvt_pk_bf16_f32 v52, v10, v10
	s_mov_b32 s13, 0xc0000
	buffer_store_short v52, v51, s[4:7], s13 offen sc1
	s_waitcnt vmcnt(32)
; __device__ __forceinline__ float bf2f(bf16 v) { return __uint_as_float(((unsigned)v) << 16); }
; __device__ __forceinline__ unsigned f2bfu(float f) { return (unsigned)__builtin_bit_cast(unsigned short, (__bf16)f); }
; __global__ void __launch_bounds__(NTHR, 2) k_main(Args a) {
;     ...
;             for (int c0 = 0; c0 < 64; c0 += 8) {
;                 float st[8], dc[8];
; #pragma unroll
;                 for (int j = 0; j < 8; ++j) { const int bch = (b * 64 + c0 + j) * 8 + h; st[j] = bf2f(__builtin_nontemporal_load(&STATES[(size_t)bch * 8192 + pn])); dc[j] = CDEC[bch]; }
; #pragma unroll
;                 for (int j = 0; j < 8; ++j) { const int bch = (b * 64 + c0 + j) * 8 + h; __builtin_amdgcn_raw_buffer_store_b16((short)f2bfu(run), rsPV, (int)(((unsigned)bch * 8192u + (unsigned)pn) * 2u), 0, 16); run = dc[j] * run + st[j]; }
;             }
	v_lshlrev_b32_e32 v134, 16, v134
	v_fmac_f32_e32 v134, s70, v10
	v_mov_b32_e32 v10, v134
	v_cvt_pk_bf16_f32 v52, v10, v10
	s_mov_b32 s13, 0xe0000
	buffer_store_short v52, v51, s[4:7], s13 offen sc1
	s_waitcnt vmcnt(32)
	v_lshlrev_b32_e32 v135, 16, v135
	v_fmac_f32_e32 v135, s71, v10
	v_mov_b32_e32 v10, v135
	v_cvt_pk_bf16_f32 v52, v10, v10
	s_mov_b32 s13, 0x100000
	buffer_store_short v52, v51, s[4:7], s13 offen sc1
	s_waitcnt vmcnt(32)
	v_lshlrev_b32_e32 v136, 16, v136
	v_fmac_f32_e32 v136, s72, v10
	v_mov_b32_e32 v10, v136
	v_cvt_pk_bf16_f32 v52, v10, v10
	s_mov_b32 s13, 0x120000
	buffer_store_short v52, v51, s[4:7], s13 offen sc1
	s_waitcnt vmcnt(32)
	v_lshlrev_b32_e32 v137, 16, v137
	v_fmac_f32_e32 v137, s73, v10
	v_mov_b32_e32 v10, v137
	v_cvt_pk_bf16_f32 v52, v10, v10
	s_mov_b32 s13, 0x140000
	buffer_store_short v52, v51, s[4:7], s13 offen sc1
	s_waitcnt vmcnt(32)
	v_lshlrev_b32_e32 v138, 16, v138
	v_fmac_f32_e32 v138, s74, v10
	v_mov_b32_e32 v10, v138
	v_cvt_pk_bf16_f32 v52, v10, v10
	s_mov_b32 s13, 0x160000
	buffer_store_short v52, v51, s[4:7], s13 offen sc1
	s_waitcnt vmcnt(32)
	v_lshlrev_b32_e32 v139, 16, v139
	v_fmac_f32_e32 v139, s75, v10
	v_mov_b32_e32 v10, v139
	v_cvt_pk_bf16_f32 v52, v10, v10
	s_mov_b32 s13, 0x180000
	buffer_store_short v52, v51, s[4:7], s13 offen sc1
	s_waitcnt vmcnt(32)
	v_lshlrev_b32_e32 v140, 16, v140
	v_fmac_f32_e32 v140, s76, v10
	v_mov_b32_e32 v10, v140
	v_cvt_pk_bf16_f32 v52, v10, v10
	s_mov_b32 s13, 0x1a0000
	buffer_store_short v52, v51, s[4:7], s13 offen sc1
	s_waitcnt vmcnt(32)
	v_lshlrev_b32_e32 v141, 16, v141
	v_fmac_f32_e32 v141, s77, v10
	v_mov_b32_e32 v10, v141
	v_cvt_pk_bf16_f32 v52, v10, v10
	s_mov_b32 s13, 0x1c0000
	buffer_store_short v52, v51, s[4:7], s13 offen sc1
	s_waitcnt vmcnt(32)
	v_lshlrev_b32_e32 v142, 16, v142
	v_fmac_f32_e32 v142, s78, v10
	v_mov_b32_e32 v10, v142
	v_cvt_pk_bf16_f32 v52, v10, v10
	s_mov_b32 s13, 0x1e0000
	buffer_store_short v52, v51, s[4:7], s13 offen sc1
	s_waitcnt vmcnt(32)
	v_lshlrev_b32_e32 v143, 16, v143
	v_fmac_f32_e32 v143, s79, v10
	v_mov_b32_e32 v10, v143
	v_add_u32_e32 v53, 0x400000, v47
	global_load_ushort v128, v53, s[58:59] nt
	v_add_u32_e32 v53, 0x420000, v47
	global_load_ushort v129, v53, s[58:59] nt
	v_add_u32_e32 v53, 0x440000, v47
	global_load_ushort v130, v53, s[58:59] nt
	v_add_u32_e32 v53, 0x460000, v47
	global_load_ushort v131, v53, s[58:59] nt
	v_add_u32_e32 v53, 0x480000, v47
	global_load_ushort v132, v53, s[58:59] nt
	v_add_u32_e32 v53, 0x4a0000, v47
	global_load_ushort v133, v53, s[58:59] nt
	v_add_u32_e32 v53, 0x4c0000, v47
	global_load_ushort v134, v53, s[58:59] nt
	v_add_u32_e32 v53, 0x4e0000, v47
	global_load_ushort v135, v53, s[58:59] nt
	v_add_u32_e32 v53, 0x500000, v47
	global_load_ushort v136, v53, s[58:59] nt
	v_add_u32_e32 v53, 0x520000, v47
	global_load_ushort v137, v53, s[58:59] nt
	v_add_u32_e32 v53, 0x540000, v47
	global_load_ushort v138, v53, s[58:59] nt
	v_add_u32_e32 v53, 0x560000, v47
	global_load_ushort v139, v53, s[58:59] nt
	v_add_u32_e32 v53, 0x580000, v47
	global_load_ushort v140, v53, s[58:59] nt
	v_add_u32_e32 v53, 0x5a0000, v47
	global_load_ushort v141, v53, s[58:59] nt
	v_add_u32_e32 v53, 0x5c0000, v47
	global_load_ushort v142, v53, s[58:59] nt
	v_add_u32_e32 v53, 0x5e0000, v47
	global_load_ushort v143, v53, s[58:59] nt
	s_waitcnt lgkmcnt(0)
	s_load_dword s64, s[46:47], 0x400
	s_load_dword s65, s[46:47], 0x420
	s_load_dword s66, s[46:47], 0x440
	s_load_dword s67, s[46:47], 0x460
	s_load_dword s68, s[46:47], 0x480
	s_load_dword s69, s[46:47], 0x4a0
	s_load_dword s70, s[46:47], 0x4c0
	s_load_dword s71, s[46:47], 0x4e0
	s_load_dword s72, s[46:47], 0x500
	s_load_dword s73, s[46:47], 0x520
	s_load_dword s74, s[46:47], 0x540
	s_load_dword s75, s[46:47], 0x560
	s_load_dword s76, s[46:47], 0x580
	s_load_dword s77, s[46:47], 0x5a0
	s_load_dword s78, s[46:47], 0x5c0
	s_load_dword s79, s[46:47], 0x5e0
	v_cvt_pk_bf16_f32 v52, v10, v10
	s_mov_b32 s13, 0x200000
	buffer_store_short v52, v51, s[4:7], s13 offen sc1
	s_waitcnt vmcnt(48)
	v_lshlrev_b32_e32 v144, 16, v144
	v_fmac_f32_e32 v144, s21, v10
	v_mov_b32_e32 v10, v144
	v_cvt_pk_bf16_f32 v52, v10, v10
	s_mov_b32 s13, 0x220000
	buffer_store_short v52, v51, s[4:7], s13 offen sc1
	s_waitcnt vmcnt(48)
	v_lshlrev_b32_e32 v145, 16, v145
	v_fmac_f32_e32 v145, s22, v10
	v_mov_b32_e32 v10, v145
	v_cvt_pk_bf16_f32 v52, v10, v10
	s_mov_b32 s13, 0x240000
	buffer_store_short v52, v51, s[4:7], s13 offen sc1
	s_waitcnt vmcnt(48)
	v_lshlrev_b32_e32 v146, 16, v146
	v_fmac_f32_e32 v146, s23, v10
	v_mov_b32_e32 v10, v146
	v_cvt_pk_bf16_f32 v52, v10, v10
	s_mov_b32 s13, 0x260000
	buffer_store_short v52, v51, s[4:7], s13 offen sc1
	s_waitcnt vmcnt(48)
	v_lshlrev_b32_e32 v147, 16, v147
	v_fmac_f32_e32 v147, s24, v10
	v_mov_b32_e32 v10, v147
	v_cvt_pk_bf16_f32 v52, v10, v10
	s_mov_b32 s13, 0x280000
	buffer_store_short v52, v51, s[4:7], s13 offen sc1
	s_waitcnt vmcnt(48)
	v_lshlrev_b32_e32 v148, 16, v148
	v_fmac_f32_e32 v148, s25, v10
	v_mov_b32_e32 v10, v148
	v_cvt_pk_bf16_f32 v52, v10, v10
	s_mov_b32 s13, 0x2a0000
	buffer_store_short v52, v51, s[4:7], s13 offen sc1
	s_waitcnt vmcnt(48)
	v_lshlrev_b32_e32 v149, 16, v149
	v_fmac_f32_e32 v149, s26, v10
	v_mov_b32_e32 v10, v149
	v_cvt_pk_bf16_f32 v52, v10, v10
	s_mov_b32 s13, 0x2c0000
	buffer_store_short v52, v51, s[4:7], s13 offen sc1
	s_waitcnt vmcnt(48)
	v_lshlrev_b32_e32 v150, 16, v150
	v_fmac_f32_e32 v150, s27, v10
	v_mov_b32_e32 v10, v150
	v_cvt_pk_bf16_f32 v52, v10, v10
	s_mov_b32 s13, 0x2e0000
	buffer_store_short v52, v51, s[4:7], s13 offen sc1
	s_waitcnt vmcnt(48)
; __device__ __forceinline__ float bf2f(bf16 v) { return __uint_as_float(((unsigned)v) << 16); }
; __device__ __forceinline__ unsigned f2bfu(float f) { return (unsigned)__builtin_bit_cast(unsigned short, (__bf16)f); }
; __global__ void __launch_bounds__(NTHR, 2) k_main(Args a) {
;     ...
;             for (int c0 = 0; c0 < 64; c0 += 8) {
;                 float st[8], dc[8];
; #pragma unroll
;                 for (int j = 0; j < 8; ++j) { const int bch = (b * 64 + c0 + j) * 8 + h; st[j] = bf2f(__builtin_nontemporal_load(&STATES[(size_t)bch * 8192 + pn])); dc[j] = CDEC[bch]; }
; #pragma unroll
;                 for (int j = 0; j < 8; ++j) { const int bch = (b * 64 + c0 + j) * 8 + h; __builtin_amdgcn_raw_buffer_store_b16((short)f2bfu(run), rsPV, (int)(((unsigned)bch * 8192u + (unsigned)pn) * 2u), 0, 16); run = dc[j] * run + st[j]; }
;             }
	v_lshlrev_b32_e32 v151, 16, v151
	v_fmac_f32_e32 v151, s37, v10
	v_mov_b32_e32 v10, v151
	v_cvt_pk_bf16_f32 v52, v10, v10
	s_mov_b32 s13, 0x300000
	buffer_store_short v52, v51, s[4:7], s13 offen sc1
	s_waitcnt vmcnt(48)
	v_lshlrev_b32_e32 v152, 16, v152
	v_fmac_f32_e32 v152, s38, v10
	v_mov_b32_e32 v10, v152
	v_cvt_pk_bf16_f32 v52, v10, v10
	s_mov_b32 s13, 0x320000
	buffer_store_short v52, v51, s[4:7], s13 offen sc1
	s_waitcnt vmcnt(48)
	v_lshlrev_b32_e32 v153, 16, v153
	v_fmac_f32_e32 v153, s39, v10
	v_mov_b32_e32 v10, v153
	v_cvt_pk_bf16_f32 v52, v10, v10
	s_mov_b32 s13, 0x340000
	buffer_store_short v52, v51, s[4:7], s13 offen sc1
	s_waitcnt vmcnt(48)
	v_lshlrev_b32_e32 v154, 16, v154
	v_fmac_f32_e32 v154, s40, v10
	v_mov_b32_e32 v10, v154
	v_cvt_pk_bf16_f32 v52, v10, v10
	s_mov_b32 s13, 0x360000
	buffer_store_short v52, v51, s[4:7], s13 offen sc1
	s_waitcnt vmcnt(48)
	v_lshlrev_b32_e32 v155, 16, v155
	v_fmac_f32_e32 v155, s41, v10
	v_mov_b32_e32 v10, v155
	v_cvt_pk_bf16_f32 v52, v10, v10
	s_mov_b32 s13, 0x380000
	buffer_store_short v52, v51, s[4:7], s13 offen sc1
	s_waitcnt vmcnt(48)
	v_lshlrev_b32_e32 v156, 16, v156
	v_fmac_f32_e32 v156, s45, v10
	v_mov_b32_e32 v10, v156
	v_cvt_pk_bf16_f32 v52, v10, v10
	s_mov_b32 s13, 0x3a0000
	buffer_store_short v52, v51, s[4:7], s13 offen sc1
	s_waitcnt vmcnt(48)
	v_lshlrev_b32_e32 v157, 16, v157
	v_fmac_f32_e32 v157, s48, v10
	v_mov_b32_e32 v10, v157
	v_cvt_pk_bf16_f32 v52, v10, v10
	s_mov_b32 s13, 0x3c0000
	buffer_store_short v52, v51, s[4:7], s13 offen sc1
	s_waitcnt vmcnt(48)
	v_lshlrev_b32_e32 v158, 16, v158
	v_fmac_f32_e32 v158, s49, v10
	v_mov_b32_e32 v10, v158
	v_cvt_pk_bf16_f32 v52, v10, v10
	s_mov_b32 s13, 0x3e0000
	buffer_store_short v52, v51, s[4:7], s13 offen sc1
	s_waitcnt vmcnt(48)
	v_lshlrev_b32_e32 v159, 16, v159
	v_fmac_f32_e32 v159, s32, v10
	v_mov_b32_e32 v10, v159
	v_add_u32_e32 v53, 0x600000, v47
	global_load_ushort v144, v53, s[58:59] nt
	v_add_u32_e32 v53, 0x620000, v47
	global_load_ushort v145, v53, s[58:59] nt
	v_add_u32_e32 v53, 0x640000, v47
	global_load_ushort v146, v53, s[58:59] nt
	v_add_u32_e32 v53, 0x660000, v47
	global_load_ushort v147, v53, s[58:59] nt
	v_add_u32_e32 v53, 0x680000, v47
	global_load_ushort v148, v53, s[58:59] nt
	v_add_u32_e32 v53, 0x6a0000, v47
	global_load_ushort v149, v53, s[58:59] nt
	v_add_u32_e32 v53, 0x6c0000, v47
	global_load_ushort v150, v53, s[58:59] nt
	v_add_u32_e32 v53, 0x6e0000, v47
	global_load_ushort v151, v53, s[58:59] nt
	v_add_u32_e32 v53, 0x700000, v47
	global_load_ushort v152, v53, s[58:59] nt
	v_add_u32_e32 v53, 0x720000, v47
	global_load_ushort v153, v53, s[58:59] nt
	v_add_u32_e32 v53, 0x740000, v47
	global_load_ushort v154, v53, s[58:59] nt
	v_add_u32_e32 v53, 0x760000, v47
	global_load_ushort v155, v53, s[58:59] nt
	v_add_u32_e32 v53, 0x780000, v47
	global_load_ushort v156, v53, s[58:59] nt
	v_add_u32_e32 v53, 0x7a0000, v47
	global_load_ushort v157, v53, s[58:59] nt
	v_add_u32_e32 v53, 0x7c0000, v47
	global_load_ushort v158, v53, s[58:59] nt
	v_add_u32_e32 v53, 0x7e0000, v47
	global_load_ushort v159, v53, s[58:59] nt
	s_waitcnt lgkmcnt(0)
	s_load_dword s21, s[46:47], 0x600
	s_load_dword s22, s[46:47], 0x620
	s_load_dword s23, s[46:47], 0x640
	s_load_dword s24, s[46:47], 0x660
	s_load_dword s25, s[46:47], 0x680
	s_load_dword s26, s[46:47], 0x6a0
	s_load_dword s27, s[46:47], 0x6c0
	s_load_dword s37, s[46:47], 0x6e0
	s_load_dword s38, s[46:47], 0x700
	s_load_dword s39, s[46:47], 0x720
	s_load_dword s40, s[46:47], 0x740
	s_load_dword s41, s[46:47], 0x760
	s_load_dword s45, s[46:47], 0x780
	s_load_dword s48, s[46:47], 0x7a0
	s_load_dword s49, s[46:47], 0x7c0
	s_load_dword s32, s[46:47], 0x7e0
	v_cvt_pk_bf16_f32 v52, v10, v10
	s_mov_b32 s13, 0x400000
	buffer_store_short v52, v51, s[4:7], s13 offen sc1
	s_waitcnt vmcnt(48)
	v_lshlrev_b32_e32 v128, 16, v128
	v_fmac_f32_e32 v128, s64, v10
	v_mov_b32_e32 v10, v128
	v_cvt_pk_bf16_f32 v52, v10, v10
	s_mov_b32 s13, 0x420000
	buffer_store_short v52, v51, s[4:7], s13 offen sc1
	s_waitcnt vmcnt(48)
	v_lshlrev_b32_e32 v129, 16, v129
	v_fmac_f32_e32 v129, s65, v10
	v_mov_b32_e32 v10, v129
	v_cvt_pk_bf16_f32 v52, v10, v10
	s_mov_b32 s13, 0x440000
	buffer_store_short v52, v51, s[4:7], s13 offen sc1
	s_waitcnt vmcnt(48)
	v_lshlrev_b32_e32 v130, 16, v130
	v_fmac_f32_e32 v130, s66, v10
	v_mov_b32_e32 v10, v130
	v_cvt_pk_bf16_f32 v52, v10, v10
	s_mov_b32 s13, 0x460000
	buffer_store_short v52, v51, s[4:7], s13 offen sc1
	s_waitcnt vmcnt(48)
	v_lshlrev_b32_e32 v131, 16, v131
	v_fmac_f32_e32 v131, s67, v10
	v_mov_b32_e32 v10, v131
	v_cvt_pk_bf16_f32 v52, v10, v10
	s_mov_b32 s13, 0x480000
	buffer_store_short v52, v51, s[4:7], s13 offen sc1
	s_waitcnt vmcnt(48)
	v_lshlrev_b32_e32 v132, 16, v132
	v_fmac_f32_e32 v132, s68, v10
	v_mov_b32_e32 v10, v132
	v_cvt_pk_bf16_f32 v52, v10, v10
	s_mov_b32 s13, 0x4a0000
	buffer_store_short v52, v51, s[4:7], s13 offen sc1
	s_waitcnt vmcnt(48)
	v_lshlrev_b32_e32 v133, 16, v133
	v_fmac_f32_e32 v133, s69, v10
	v_mov_b32_e32 v10, v133
	v_cvt_pk_bf16_f32 v52, v10, v10
	s_mov_b32 s13, 0x4c0000
	buffer_store_short v52, v51, s[4:7], s13 offen sc1
	s_waitcnt vmcnt(48)
	v_lshlrev_b32_e32 v134, 16, v134
	v_fmac_f32_e32 v134, s70, v10
	v_mov_b32_e32 v10, v134
	v_cvt_pk_bf16_f32 v52, v10, v10
	s_mov_b32 s13, 0x4e0000
	buffer_store_short v52, v51, s[4:7], s13 offen sc1
	s_waitcnt vmcnt(48)
	v_lshlrev_b32_e32 v135, 16, v135
	v_fmac_f32_e32 v135, s71, v10
	v_mov_b32_e32 v10, v135
	v_cvt_pk_bf16_f32 v52, v10, v10
	s_mov_b32 s13, 0x500000
	buffer_store_short v52, v51, s[4:7], s13 offen sc1
	s_waitcnt vmcnt(48)
; __device__ __forceinline__ float bf2f(bf16 v) { return __uint_as_float(((unsigned)v) << 16); }
; __device__ __forceinline__ unsigned f2bfu(float f) { return (unsigned)__builtin_bit_cast(unsigned short, (__bf16)f); }
; __global__ void __launch_bounds__(NTHR, 2) k_main(Args a) {
;     ...
;             for (int c0 = 0; c0 < 64; c0 += 8) {
;                 float st[8], dc[8];
; #pragma unroll
;                 for (int j = 0; j < 8; ++j) { const int bch = (b * 64 + c0 + j) * 8 + h; st[j] = bf2f(__builtin_nontemporal_load(&STATES[(size_t)bch * 8192 + pn])); dc[j] = CDEC[bch]; }
; #pragma unroll
;                 for (int j = 0; j < 8; ++j) { const int bch = (b * 64 + c0 + j) * 8 + h; __builtin_amdgcn_raw_buffer_store_b16((short)f2bfu(run), rsPV, (int)(((unsigned)bch * 8192u + (unsigned)pn) * 2u), 0, 16); run = dc[j] * run + st[j]; }
;             }
;         }
	v_lshlrev_b32_e32 v136, 16, v136
	v_fmac_f32_e32 v136, s72, v10
	v_mov_b32_e32 v10, v136
	v_cvt_pk_bf16_f32 v52, v10, v10
	s_mov_b32 s13, 0x520000
	buffer_store_short v52, v51, s[4:7], s13 offen sc1
	s_waitcnt vmcnt(48)
	v_lshlrev_b32_e32 v137, 16, v137
	v_fmac_f32_e32 v137, s73, v10
	v_mov_b32_e32 v10, v137
	v_cvt_pk_bf16_f32 v52, v10, v10
	s_mov_b32 s13, 0x540000
	buffer_store_short v52, v51, s[4:7], s13 offen sc1
	s_waitcnt vmcnt(48)
	v_lshlrev_b32_e32 v138, 16, v138
	v_fmac_f32_e32 v138, s74, v10
	v_mov_b32_e32 v10, v138
	v_cvt_pk_bf16_f32 v52, v10, v10
	s_mov_b32 s13, 0x560000
	buffer_store_short v52, v51, s[4:7], s13 offen sc1
	s_waitcnt vmcnt(48)
	v_lshlrev_b32_e32 v139, 16, v139
	v_fmac_f32_e32 v139, s75, v10
	v_mov_b32_e32 v10, v139
	v_cvt_pk_bf16_f32 v52, v10, v10
	s_mov_b32 s13, 0x580000
	buffer_store_short v52, v51, s[4:7], s13 offen sc1
	s_waitcnt vmcnt(48)
	v_lshlrev_b32_e32 v140, 16, v140
	v_fmac_f32_e32 v140, s76, v10
	v_mov_b32_e32 v10, v140
	v_cvt_pk_bf16_f32 v52, v10, v10
	s_mov_b32 s13, 0x5a0000
	buffer_store_short v52, v51, s[4:7], s13 offen sc1
	s_waitcnt vmcnt(48)
	v_lshlrev_b32_e32 v141, 16, v141
	v_fmac_f32_e32 v141, s77, v10
	v_mov_b32_e32 v10, v141
	v_cvt_pk_bf16_f32 v52, v10, v10
	s_mov_b32 s13, 0x5c0000
	buffer_store_short v52, v51, s[4:7], s13 offen sc1
	s_waitcnt vmcnt(48)
	v_lshlrev_b32_e32 v142, 16, v142
	v_fmac_f32_e32 v142, s78, v10
	v_mov_b32_e32 v10, v142
	v_cvt_pk_bf16_f32 v52, v10, v10
	s_mov_b32 s13, 0x5e0000
	buffer_store_short v52, v51, s[4:7], s13 offen sc1
	s_waitcnt vmcnt(48)
	v_lshlrev_b32_e32 v143, 16, v143
	v_fmac_f32_e32 v143, s79, v10
	v_mov_b32_e32 v10, v143
	s_waitcnt lgkmcnt(0)
	v_cvt_pk_bf16_f32 v52, v10, v10
	s_mov_b32 s13, 0x600000
	buffer_store_short v52, v51, s[4:7], s13 offen sc1
	s_waitcnt vmcnt(32)
	v_lshlrev_b32_e32 v144, 16, v144
	v_fmac_f32_e32 v144, s21, v10
	v_mov_b32_e32 v10, v144
	v_cvt_pk_bf16_f32 v52, v10, v10
	s_mov_b32 s13, 0x620000
	buffer_store_short v52, v51, s[4:7], s13 offen sc1
	s_waitcnt vmcnt(32)
	v_lshlrev_b32_e32 v145, 16, v145
	v_fmac_f32_e32 v145, s22, v10
	v_mov_b32_e32 v10, v145
	v_cvt_pk_bf16_f32 v52, v10, v10
	s_mov_b32 s13, 0x640000
	buffer_store_short v52, v51, s[4:7], s13 offen sc1
	s_waitcnt vmcnt(32)
	v_lshlrev_b32_e32 v146, 16, v146
	v_fmac_f32_e32 v146, s23, v10
	v_mov_b32_e32 v10, v146
	v_cvt_pk_bf16_f32 v52, v10, v10
	s_mov_b32 s13, 0x660000
	buffer_store_short v52, v51, s[4:7], s13 offen sc1
	s_waitcnt vmcnt(32)
	v_lshlrev_b32_e32 v147, 16, v147
	v_fmac_f32_e32 v147, s24, v10
	v_mov_b32_e32 v10, v147
	v_cvt_pk_bf16_f32 v52, v10, v10
	s_mov_b32 s13, 0x680000
	buffer_store_short v52, v51, s[4:7], s13 offen sc1
	s_waitcnt vmcnt(32)
	v_lshlrev_b32_e32 v148, 16, v148
	v_fmac_f32_e32 v148, s25, v10
	v_mov_b32_e32 v10, v148
	v_cvt_pk_bf16_f32 v52, v10, v10
	s_mov_b32 s13, 0x6a0000
	buffer_store_short v52, v51, s[4:7], s13 offen sc1
	s_waitcnt vmcnt(32)
	v_lshlrev_b32_e32 v149, 16, v149
	v_fmac_f32_e32 v149, s26, v10
	v_mov_b32_e32 v10, v149
	v_cvt_pk_bf16_f32 v52, v10, v10
	s_mov_b32 s13, 0x6c0000
	buffer_store_short v52, v51, s[4:7], s13 offen sc1
	s_waitcnt vmcnt(32)
	v_lshlrev_b32_e32 v150, 16, v150
	v_fmac_f32_e32 v150, s27, v10
	v_mov_b32_e32 v10, v150
	v_cvt_pk_bf16_f32 v52, v10, v10
	s_mov_b32 s13, 0x6e0000
	buffer_store_short v52, v51, s[4:7], s13 offen sc1
	s_waitcnt vmcnt(32)
	v_lshlrev_b32_e32 v151, 16, v151
	v_fmac_f32_e32 v151, s37, v10
	v_mov_b32_e32 v10, v151
	v_cvt_pk_bf16_f32 v52, v10, v10
	s_mov_b32 s13, 0x700000
	buffer_store_short v52, v51, s[4:7], s13 offen sc1
	s_waitcnt vmcnt(32)
	v_lshlrev_b32_e32 v152, 16, v152
	v_fmac_f32_e32 v152, s38, v10
	v_mov_b32_e32 v10, v152
	v_cvt_pk_bf16_f32 v52, v10, v10
	s_mov_b32 s13, 0x720000
	buffer_store_short v52, v51, s[4:7], s13 offen sc1
	s_waitcnt vmcnt(32)
	v_lshlrev_b32_e32 v153, 16, v153
	v_fmac_f32_e32 v153, s39, v10
	v_mov_b32_e32 v10, v153
	v_cvt_pk_bf16_f32 v52, v10, v10
	s_mov_b32 s13, 0x740000
	buffer_store_short v52, v51, s[4:7], s13 offen sc1
	s_waitcnt vmcnt(32)
	v_lshlrev_b32_e32 v154, 16, v154
	v_fmac_f32_e32 v154, s40, v10
	v_mov_b32_e32 v10, v154
	v_cvt_pk_bf16_f32 v52, v10, v10
	s_mov_b32 s13, 0x760000
	buffer_store_short v52, v51, s[4:7], s13 offen sc1
	s_waitcnt vmcnt(32)
	v_lshlrev_b32_e32 v155, 16, v155
	v_fmac_f32_e32 v155, s41, v10
	v_mov_b32_e32 v10, v155
	v_cvt_pk_bf16_f32 v52, v10, v10
	s_mov_b32 s13, 0x780000
	buffer_store_short v52, v51, s[4:7], s13 offen sc1
	s_waitcnt vmcnt(32)
	v_lshlrev_b32_e32 v156, 16, v156
	v_fmac_f32_e32 v156, s45, v10
	v_mov_b32_e32 v10, v156
	v_cvt_pk_bf16_f32 v52, v10, v10
	s_mov_b32 s13, 0x7a0000
	buffer_store_short v52, v51, s[4:7], s13 offen sc1
	s_waitcnt vmcnt(32)
	v_lshlrev_b32_e32 v157, 16, v157
	v_fmac_f32_e32 v157, s48, v10
	v_mov_b32_e32 v10, v157
	v_cvt_pk_bf16_f32 v52, v10, v10
	s_mov_b32 s13, 0x7c0000
	buffer_store_short v52, v51, s[4:7], s13 offen sc1
	s_waitcnt vmcnt(32)
	v_lshlrev_b32_e32 v158, 16, v158
	v_fmac_f32_e32 v158, s49, v10
	v_mov_b32_e32 v10, v158
	v_cvt_pk_bf16_f32 v52, v10, v10
	s_mov_b32 s13, 0x7e0000
	buffer_store_short v52, v51, s[4:7], s13 offen sc1
	s_waitcnt vmcnt(32)
	v_lshlrev_b32_e32 v159, 16, v159
	v_fmac_f32_e32 v159, s32, v10
	v_mov_b32_e32 v10, v159
	v_add_u32_e32 v8, s56, v8
	v_cmp_lt_i32_e32 vcc, s11, v8
	s_or_b64 s[8:9], vcc, s[8:9]
	v_add_u32_e32 v9, s3, v9
	s_andn2_b64 exec, exec, s[8:9]
	s_cbranch_execnz .LBB0_377
